# HGRN chunk-state pass: V tile loads hoisted to item top (on top of HGRN outputs-pass V/S/epilogue hoist)
# baseline (speedup 1.0000x reference)
.LBB0_548:
	s_or_b64 exec, exec, s[0:1]
	s_waitcnt lgkmcnt(0)
	s_barrier
	ds_read_b32 v0, v3 offset:16
	s_movk_i32 s0, 0x10ff
	s_waitcnt lgkmcnt(0)
	v_cmp_lt_i32_e32 vcc, s0, v0
	v_readfirstlane_b32 s6, v0
	s_mov_b64 s[0:1], -1
	s_cbranch_vccnz .LBB0_543
	s_cmpk_gt_i32 s6, 0x43f
	s_cbranch_scc0 .LBB0_760
	s_cmpk_gt_u32 s6, 0x65f
	s_cbranch_scc0 .LBB0_719
	s_cmpk_gt_u32 s6, 0x87f
	s_cbranch_scc0 .LBB0_561
	s_add_i32 s0, s6, 0xf780
	s_and_b32 s1, s0, 0xffff
	s_mul_i32 s5, s1, 0xf0f1
	s_lshr_b32 s7, s5, 22
	s_mulk_i32 s7, 0x44
	s_sub_i32 s0, s0, s7
	s_lshr_b32 s4, s5, 24
	s_and_b32 s7, s0, 0xffff
	s_mul_i32 s1, s4, 0xee0000
	s_mul_i32 s0, s7, 0x38000
	s_add_i32 s22, s1, s0
	v_mov_b32_e32 v0, v222
	s_lshl_b64 s[0:1], s[22:23], 1
	s_add_u32 s0, s24, s0
	s_addc_u32 s1, s25, s1
	s_bfe_u32 s5, s5, 0x20016
	v_mov_b32_e32 v0, v222
	s_lshl_b32 s10, s5, 6
	v_and_b32_e32 v6, 63, v0
	v_ashrrev_i32_e32 v4, 6, v0
	v_or_b32_e32 v1, s10, v6
	v_lshlrev_b32_e32 v24, 4, v4
	v_lshlrev_b32_e32 v2, 1, v1
	v_lshl_add_u64 v[8:9], s[0:1], 0, v[2:3]
	v_or_b32_e32 v2, 2, v24
	v_or_b32_e32 v1, 1, v24
	v_mad_i64_i32 v[14:15], s[12:13], v2, s48, v[8:9]
	v_or_b32_e32 v2, 3, v24
	v_mad_i64_i32 v[10:11], s[12:13], v24, s48, v[8:9]
	v_mad_i64_i32 v[12:13], s[12:13], v1, s48, v[8:9]
	v_mad_i64_i32 v[16:17], s[12:13], v2, s48, v[8:9]
	s_barrier
	v_mad_i64_i32 v[128:129], s[12:13], v24, s48, v[8:9]
	global_load_ushort v96, v[128:129], off offset:1024
	global_load_ushort v80, v[128:129], off offset:2560
	v_or_b32_e32 v137, 1, v24
	v_mad_i64_i32 v[130:131], s[12:13], v137, s48, v[8:9]
	global_load_ushort v97, v[130:131], off offset:1024
	global_load_ushort v81, v[130:131], off offset:2560
	v_or_b32_e32 v138, 2, v24
	v_mad_i64_i32 v[132:133], s[12:13], v138, s48, v[8:9]
	global_load_ushort v98, v[132:133], off offset:1024
	global_load_ushort v82, v[132:133], off offset:2560
	v_or_b32_e32 v139, 3, v24
	v_mad_i64_i32 v[134:135], s[12:13], v139, s48, v[8:9]
	global_load_ushort v99, v[134:135], off offset:1024
	global_load_ushort v83, v[134:135], off offset:2560
	v_or_b32_e32 v136, 4, v24
	v_mad_i64_i32 v[128:129], s[12:13], v136, s48, v[8:9]
	global_load_ushort v100, v[128:129], off offset:1024
	global_load_ushort v84, v[128:129], off offset:2560
	v_or_b32_e32 v137, 5, v24
	v_mad_i64_i32 v[130:131], s[12:13], v137, s48, v[8:9]
	global_load_ushort v101, v[130:131], off offset:1024
	global_load_ushort v85, v[130:131], off offset:2560
	v_or_b32_e32 v138, 6, v24
	v_mad_i64_i32 v[132:133], s[12:13], v138, s48, v[8:9]
	global_load_ushort v102, v[132:133], off offset:1024
	global_load_ushort v86, v[132:133], off offset:2560
	v_or_b32_e32 v139, 7, v24
	v_mad_i64_i32 v[134:135], s[12:13], v139, s48, v[8:9]
	global_load_ushort v103, v[134:135], off offset:1024
	global_load_ushort v87, v[134:135], off offset:2560
	v_or_b32_e32 v136, 8, v24
	v_mad_i64_i32 v[128:129], s[12:13], v136, s48, v[8:9]
	global_load_ushort v104, v[128:129], off offset:1024
	global_load_ushort v88, v[128:129], off offset:2560
	v_or_b32_e32 v137, 9, v24
	v_mad_i64_i32 v[130:131], s[12:13], v137, s48, v[8:9]
	global_load_ushort v105, v[130:131], off offset:1024
	global_load_ushort v89, v[130:131], off offset:2560
	v_or_b32_e32 v138, 10, v24
	v_mad_i64_i32 v[132:133], s[12:13], v138, s48, v[8:9]
	global_load_ushort v106, v[132:133], off offset:1024
	global_load_ushort v90, v[132:133], off offset:2560
	v_or_b32_e32 v139, 11, v24
	v_mad_i64_i32 v[134:135], s[12:13], v139, s48, v[8:9]
	global_load_ushort v107, v[134:135], off offset:1024
	global_load_ushort v91, v[134:135], off offset:2560
	v_or_b32_e32 v136, 12, v24
	v_mad_i64_i32 v[128:129], s[12:13], v136, s48, v[8:9]
	global_load_ushort v108, v[128:129], off offset:1024
	global_load_ushort v92, v[128:129], off offset:2560
	v_or_b32_e32 v137, 13, v24
	v_mad_i64_i32 v[130:131], s[12:13], v137, s48, v[8:9]
	global_load_ushort v109, v[130:131], off offset:1024
	global_load_ushort v93, v[130:131], off offset:2560
	v_or_b32_e32 v138, 14, v24
	v_mad_i64_i32 v[132:133], s[12:13], v138, s48, v[8:9]
	global_load_ushort v110, v[132:133], off offset:1024
	global_load_ushort v94, v[132:133], off offset:2560
	v_or_b32_e32 v139, 15, v24
	v_mad_i64_i32 v[134:135], s[12:13], v139, s48, v[8:9]
	global_load_ushort v111, v[134:135], off offset:1024
	global_load_ushort v95, v[134:135], off offset:2560
	v_lshrrev_b32_e32 v180, 3, v222
	v_mul_u32_u24_e32 v180, 0x1c00, v180
	v_lshlrev_b32_e32 v181, 4, v222
	v_and_b32_e32 v181, 0x70, v181
	s_lshl_b32 s99, s5, 7
	v_add3_u32 v180, v180, v181, s99
	global_load_dwordx4 v[140:143], v180, s[0:1] offset:1536
	v_add_u32_e32 v181, 0x38000, v180
	global_load_dwordx4 v[144:147], v181, s[0:1] offset:1536
	global_load_ushort v2, v[10:11], off offset:2048
	global_load_ushort v5, v[12:13], off offset:2048
	global_load_ushort v7, v[14:15], off offset:2048
	global_load_ushort v18, v[16:17], off offset:2048
	global_load_ushort v19, v[16:17], off offset:1024
	global_load_ushort v20, v[14:15], off offset:1024
	global_load_ushort v21, v[12:13], off offset:1024
	global_load_ushort v22, v[10:11], off offset:1024
	v_or_b32_e32 v10, 4, v24
	v_or_b32_e32 v12, 5, v24
	v_or_b32_e32 v14, 6, v24
	v_or_b32_e32 v16, 7, v24
	v_mad_i64_i32 v[10:11], s[12:13], v10, s48, v[8:9]
	v_mad_i64_i32 v[12:13], s[12:13], v12, s48, v[8:9]
	v_mad_i64_i32 v[14:15], s[12:13], v14, s48, v[8:9]
	v_mad_i64_i32 v[16:17], s[12:13], v16, s48, v[8:9]
	global_load_ushort v23, v[10:11], off offset:2048
	global_load_ushort v25, v[12:13], off offset:2048
	global_load_ushort v26, v[14:15], off offset:2048
	global_load_ushort v27, v[16:17], off offset:2048
	global_load_ushort v28, v[16:17], off offset:1024
	global_load_ushort v29, v[14:15], off offset:1024
	global_load_ushort v30, v[12:13], off offset:1024
	global_load_ushort v31, v[10:11], off offset:1024
	v_or_b32_e32 v10, 8, v24
	v_or_b32_e32 v12, 9, v24
	v_or_b32_e32 v14, 10, v24
	v_or_b32_e32 v16, 11, v24
	v_mad_i64_i32 v[10:11], s[12:13], v10, s48, v[8:9]
	v_mad_i64_i32 v[12:13], s[12:13], v12, s48, v[8:9]
	v_mad_i64_i32 v[14:15], s[12:13], v14, s48, v[8:9]
	v_mad_i64_i32 v[16:17], s[12:13], v16, s48, v[8:9]
	global_load_ushort v32, v[10:11], off offset:2048
	global_load_ushort v33, v[12:13], off offset:2048
	global_load_ushort v34, v[14:15], off offset:2048
	global_load_ushort v35, v[16:17], off offset:2048
	s_nop 0
	global_load_ushort v16, v[16:17], off offset:1024
	s_nop 0
	global_load_ushort v17, v[14:15], off offset:1024
	global_load_ushort v36, v[12:13], off offset:1024
	global_load_ushort v37, v[10:11], off offset:1024
	v_or_b32_e32 v10, 12, v24
	v_or_b32_e32 v12, 13, v24
	v_or_b32_e32 v14, 14, v24
	v_or_b32_e32 v38, 15, v24
	v_mad_i64_i32 v[10:11], s[12:13], v10, s48, v[8:9]
	v_mad_i64_i32 v[12:13], s[12:13], v12, s48, v[8:9]
	v_mad_i64_i32 v[14:15], s[12:13], v14, s48, v[8:9]
	v_mad_i64_i32 v[8:9], s[12:13], v38, s48, v[8:9]
	global_load_ushort v38, v[10:11], off offset:2048
	global_load_ushort v39, v[12:13], off offset:1024
	global_load_ushort v40, v[8:9], off offset:2048
	global_load_ushort v41, v[14:15], off offset:2048
	s_nop 0
	global_load_ushort v12, v[12:13], off offset:2048
	s_nop 0
	global_load_ushort v10, v[10:11], off offset:1024
	s_nop 0
	global_load_ushort v11, v[14:15], off offset:1024
	s_nop 0
	global_load_ushort v8, v[8:9], off offset:1024
	s_movk_i32 s8, 0x500
	s_waitcnt vmcnt(43)
	v_mul_lo_u32 v55, v4, s8
	v_or_b32_e32 v55, v55, v6
	s_movk_i32 s8, 0x50
	s_lshl_b32 s22, s5, 7
	s_lshl_b32 s4, s4, 3
	s_lshl_b32 s5, s5, 1
	s_or_b32 s11, s5, s4
	v_cmp_lt_i32_e32 vcc, 63, v0
	s_waitcnt vmcnt(31)
	v_lshlrev_b32_e32 v2, 16, v2
	s_waitcnt vmcnt(30)
	v_lshlrev_b32_e32 v5, 16, v5
	s_waitcnt vmcnt(29)
	v_lshlrev_b32_e32 v14, 16, v7
	v_add_f32_e32 v7, 0, v2
	s_waitcnt vmcnt(28)
	v_lshlrev_b32_e32 v18, 16, v18
	s_waitcnt vmcnt(26)
	v_lshlrev_b32_e32 v15, 16, v20
	s_waitcnt vmcnt(25)
	v_lshlrev_b32_e32 v13, 16, v21
	s_waitcnt vmcnt(24)
	v_lshlrev_b32_e32 v9, 16, v22
	v_mul_f32_e32 v2, 0x3fb8aa3b, v2
	v_mul_f32_e32 v54, 0x3fb8aa3b, v7
	v_exp_f32_e32 v2, v2
	v_exp_f32_e32 v54, v54
	v_lshlrev_b32_e32 v19, 16, v19
	s_waitcnt vmcnt(23)
	v_lshlrev_b32_e32 v20, 16, v23
	s_waitcnt vmcnt(22)
	v_lshlrev_b32_e32 v22, 16, v25
	s_waitcnt vmcnt(21)
	v_lshlrev_b32_e32 v25, 16, v26
	s_waitcnt vmcnt(20)
	v_lshlrev_b32_e32 v27, 16, v27
	v_sub_f32_e32 v2, 1.0, v2
	s_waitcnt vmcnt(18)
	v_lshlrev_b32_e32 v26, 16, v29
	s_waitcnt vmcnt(17)
	v_lshlrev_b32_e32 v23, 16, v30
	s_waitcnt vmcnt(16)
	v_lshlrev_b32_e32 v21, 16, v31
	v_mul_f32_e32 v9, v54, v9
	v_lshl_add_u32 v54, v55, 1, 32
	v_cvt_pk_bf16_f32 v9, v9, s0
	ds_write_b16 v54, v9
	v_lshlrev_b32_e32 v28, 16, v28
	s_waitcnt vmcnt(15)
	v_lshlrev_b32_e32 v29, 16, v32
	s_waitcnt vmcnt(14)
	v_lshlrev_b32_e32 v31, 16, v33
	s_waitcnt vmcnt(13)
	v_lshlrev_b32_e32 v33, 16, v34
	s_waitcnt vmcnt(12)
	v_lshlrev_b32_e32 v34, 16, v35
	s_waitcnt vmcnt(11)
	v_lshlrev_b32_e32 v16, 16, v16
	s_waitcnt vmcnt(10)
	v_lshlrev_b32_e32 v17, 16, v17
	s_waitcnt vmcnt(9)
	v_lshlrev_b32_e32 v32, 16, v36
	s_waitcnt vmcnt(8)
	v_lshlrev_b32_e32 v30, 16, v37
	s_waitcnt vmcnt(7)
	v_lshlrev_b32_e32 v35, 16, v38
	s_waitcnt vmcnt(6)
	v_lshlrev_b32_e32 v38, 16, v39
	s_waitcnt vmcnt(5)
	v_lshlrev_b32_e32 v40, 16, v40
	s_waitcnt vmcnt(4)
	v_lshlrev_b32_e32 v39, 16, v41
	s_waitcnt vmcnt(3)
	v_lshlrev_b32_e32 v37, 16, v12
	s_waitcnt vmcnt(2)
	v_lshlrev_b32_e32 v36, 16, v10
	s_waitcnt vmcnt(1)
	v_lshlrev_b32_e32 v41, 16, v11
	s_waitcnt vmcnt(0)
	v_lshlrev_b32_e32 v42, 16, v8
	v_add_f32_e32 v8, v7, v5
	v_add_f32_e32 v10, v8, v14
	v_add_f32_e32 v11, v10, v18
	v_add_f32_e32 v12, v11, v20
	v_add_f32_e32 v43, v12, v22
	v_add_f32_e32 v44, v43, v25
	v_add_f32_e32 v45, v44, v27
	v_add_f32_e32 v46, v45, v29
	v_add_f32_e32 v47, v46, v31
	v_add_f32_e32 v48, v47, v33
	v_add_f32_e32 v49, v48, v34
	v_add_f32_e32 v50, v49, v35
	v_add_f32_e32 v51, v50, v37
	v_add_f32_e32 v52, v51, v39
	v_add_f32_e32 v53, v52, v40
	v_sub_f32_e32 v7, v53, v7
	v_mul_f32_e32 v7, 0x3fb8aa3b, v7
	v_exp_f32_e32 v7, v7
	v_mul_f32_e32 v5, 0x3fb8aa3b, v5
	v_exp_f32_e32 v5, v5
	v_mul_f32_e32 v2, v2, v7
	v_cvt_pk_bf16_f32 v2, v2, s0
	ds_write_b16 v54, v2 offset:20480
	v_mul_f32_e32 v2, 0x3fb8aa3b, v8
	v_exp_f32_e32 v2, v2
	v_mad_u64_u32 v[6:7], s[12:13], v1, s8, v[6:7]
	v_sub_f32_e32 v5, 1.0, v5
	v_mul_f32_e32 v1, v2, v13
	v_sub_f32_e32 v2, v53, v8
	v_mul_f32_e32 v2, 0x3fb8aa3b, v2
	v_exp_f32_e32 v2, v2
	v_cvt_pk_bf16_f32 v1, v1, s0
	v_lshl_add_u32 v54, v6, 1, 32
	ds_write_b16 v54, v1
	v_mul_f32_e32 v1, v5, v2
	v_mul_f32_e32 v2, 0x3fb8aa3b, v14
	v_mul_f32_e32 v5, 0x3fb8aa3b, v10
	v_exp_f32_e32 v2, v2
	v_exp_f32_e32 v5, v5
	v_cvt_pk_bf16_f32 v1, v1, s0
	ds_write_b16 v54, v1 offset:20480
	v_sub_f32_e32 v1, 1.0, v2
	v_mul_f32_e32 v2, v5, v15
	v_sub_f32_e32 v5, v53, v10
	v_mul_f32_e32 v5, 0x3fb8aa3b, v5
	v_cvt_pk_bf16_f32 v2, v2, s0
	v_exp_f32_e32 v5, v5
	ds_write_b16 v54, v2 offset:160
	v_mul_f32_e32 v2, 0x3fb8aa3b, v18
	v_exp_f32_e32 v2, v2
	v_mul_f32_e32 v1, v1, v5
	v_cvt_pk_bf16_f32 v1, v1, s0
	ds_write_b16 v54, v1 offset:20640
	v_sub_f32_e32 v1, 1.0, v2
	v_mul_f32_e32 v2, 0x3fb8aa3b, v11
	v_exp_f32_e32 v2, v2
	v_sub_f32_e32 v5, v53, v11
	v_mul_f32_e32 v5, 0x3fb8aa3b, v5
	v_exp_f32_e32 v5, v5
	v_mul_f32_e32 v2, v2, v19
	v_cvt_pk_bf16_f32 v2, v2, s0
	ds_write_b16 v54, v2 offset:320
	v_mul_f32_e32 v1, v1, v5
	v_mul_f32_e32 v2, 0x3fb8aa3b, v20
	v_mul_f32_e32 v5, 0x3fb8aa3b, v12
	v_exp_f32_e32 v2, v2
	v_exp_f32_e32 v5, v5
	v_cvt_pk_bf16_f32 v1, v1, s0
	ds_write_b16 v54, v1 offset:20800
	v_sub_f32_e32 v1, 1.0, v2
	v_mul_f32_e32 v2, v5, v21
	v_sub_f32_e32 v5, v53, v12
	v_mul_f32_e32 v5, 0x3fb8aa3b, v5
	v_cvt_pk_bf16_f32 v2, v2, s0
	v_exp_f32_e32 v5, v5
	ds_write_b16 v54, v2 offset:480
	v_mul_f32_e32 v2, 0x3fb8aa3b, v22
	v_exp_f32_e32 v2, v2
	v_mul_f32_e32 v1, v1, v5
	v_cvt_pk_bf16_f32 v1, v1, s0
	ds_write_b16 v54, v1 offset:20960
	v_sub_f32_e32 v1, 1.0, v2
	v_mul_f32_e32 v2, 0x3fb8aa3b, v43
	v_exp_f32_e32 v2, v2
	v_sub_f32_e32 v5, v53, v43
	v_mul_f32_e32 v5, 0x3fb8aa3b, v5
	v_exp_f32_e32 v5, v5
	v_mul_f32_e32 v2, v2, v23
	v_cvt_pk_bf16_f32 v2, v2, s0
	ds_write_b16 v54, v2 offset:640
	v_mul_f32_e32 v1, v1, v5
	v_mul_f32_e32 v2, 0x3fb8aa3b, v25
	v_mul_f32_e32 v5, 0x3fb8aa3b, v44
	v_exp_f32_e32 v2, v2
	v_exp_f32_e32 v5, v5
	v_cvt_pk_bf16_f32 v1, v1, s0
	ds_write_b16 v54, v1 offset:21120
	v_sub_f32_e32 v1, 1.0, v2
	v_mul_f32_e32 v2, v5, v26
	v_sub_f32_e32 v5, v53, v44
	v_mul_f32_e32 v5, 0x3fb8aa3b, v5
	v_cvt_pk_bf16_f32 v2, v2, s0
	v_exp_f32_e32 v5, v5
	ds_write_b16 v54, v2 offset:800
	v_mul_f32_e32 v2, 0x3fb8aa3b, v27
	v_exp_f32_e32 v2, v2
	v_mul_f32_e32 v1, v1, v5
	v_cvt_pk_bf16_f32 v1, v1, s0
	ds_write_b16 v54, v1 offset:21280
	v_sub_f32_e32 v1, 1.0, v2
	v_mul_f32_e32 v2, 0x3fb8aa3b, v45
	v_exp_f32_e32 v2, v2
	v_sub_f32_e32 v5, v53, v45
	v_mul_f32_e32 v5, 0x3fb8aa3b, v5
	v_exp_f32_e32 v5, v5
	v_mul_f32_e32 v2, v2, v28
	v_cvt_pk_bf16_f32 v2, v2, s0
	ds_write_b16 v54, v2 offset:960
	v_mul_f32_e32 v1, v1, v5
	v_mul_f32_e32 v2, 0x3fb8aa3b, v29
	v_mul_f32_e32 v5, 0x3fb8aa3b, v46
	v_exp_f32_e32 v2, v2
	v_exp_f32_e32 v5, v5
	v_cvt_pk_bf16_f32 v1, v1, s0
	ds_write_b16 v54, v1 offset:21440
	v_sub_f32_e32 v1, 1.0, v2
	v_mul_f32_e32 v2, v5, v30
	v_sub_f32_e32 v5, v53, v46
	v_mul_f32_e32 v5, 0x3fb8aa3b, v5
	v_cvt_pk_bf16_f32 v2, v2, s0
	v_exp_f32_e32 v5, v5
	ds_write_b16 v54, v2 offset:1120
	v_mul_f32_e32 v2, 0x3fb8aa3b, v31
	v_exp_f32_e32 v2, v2
	v_mul_f32_e32 v1, v1, v5
	v_cvt_pk_bf16_f32 v1, v1, s0
	ds_write_b16 v54, v1 offset:21600
	v_sub_f32_e32 v1, 1.0, v2
	v_mul_f32_e32 v2, 0x3fb8aa3b, v47
	v_exp_f32_e32 v2, v2
	v_sub_f32_e32 v5, v53, v47
	v_mul_f32_e32 v5, 0x3fb8aa3b, v5
	v_exp_f32_e32 v5, v5
	v_mul_f32_e32 v2, v2, v32
	v_cvt_pk_bf16_f32 v2, v2, s0
	ds_write_b16 v54, v2 offset:1280
	v_mul_f32_e32 v1, v1, v5
	v_mul_f32_e32 v2, 0x3fb8aa3b, v33
	v_mul_f32_e32 v5, 0x3fb8aa3b, v48
	v_exp_f32_e32 v2, v2
	v_exp_f32_e32 v5, v5
	v_cvt_pk_bf16_f32 v1, v1, s0
	ds_write_b16 v54, v1 offset:21760
	v_sub_f32_e32 v1, 1.0, v2
	v_mul_f32_e32 v2, v5, v17
	v_cvt_pk_bf16_f32 v2, v2, s0
	ds_write_b16 v54, v2 offset:1440
	v_sub_f32_e32 v2, v53, v48
	v_mul_f32_e32 v2, 0x3fb8aa3b, v2
	v_exp_f32_e32 v5, v2
	v_mul_f32_e32 v2, 0x3fb8aa3b, v34
	v_ashrrev_i32_e32 v15, 3, v0
	v_mov_b64_e32 v[10:11], s[0:1]
	v_exp_f32_e32 v14, v2
	v_lshlrev_b32_e32 v2, 4, v0
	v_mad_i64_i32 v[6:7], s[12:13], v15, s48, v[10:11]
	v_add_u32_e32 v12, 0x100, v0
	v_and_b32_e32 v2, 0x70, v2
	v_lshl_add_u64 v[6:7], v[6:7], 0, s[22:23]
	v_ashrrev_i32_e32 v17, 3, v12
	v_lshl_add_u64 v[6:7], v[6:7], 0, v[2:3]
	v_mad_i64_i32 v[10:11], s[12:13], v17, s48, v[10:11]
	s_waitcnt vmcnt(0)
	v_mov_b32_e32 v6, v140
	v_mov_b32_e32 v7, v141
	v_mov_b32_e32 v8, v142
	v_mov_b32_e32 v9, v143
	v_lshl_add_u64 v[10:11], v[10:11], 0, s[22:23]
	v_lshl_add_u64 v[10:11], v[10:11], 0, v[2:3]
	v_mov_b32_e32 v10, v144
	v_mov_b32_e32 v11, v145
	v_mov_b32_e32 v12, v146
	v_mov_b32_e32 v13, v147
	v_mul_f32_e32 v1, v1, v5
	v_cvt_pk_bf16_f32 v1, v1, s0
	v_mul_f32_e32 v5, 0x3fb8aa3b, v49
	ds_write_b16 v54, v1 offset:21920
	v_sub_f32_e32 v1, 1.0, v14
	v_exp_f32_e32 v5, v5
	v_sub_f32_e32 v14, v53, v49
	v_mul_f32_e32 v14, 0x3fb8aa3b, v14
	v_exp_f32_e32 v14, v14
	v_mul_f32_e32 v5, v5, v16
	v_cvt_pk_bf16_f32 v5, v5, s0
	ds_write_b16 v54, v5 offset:1600
	v_mul_f32_e32 v1, v1, v14
	v_mul_f32_e32 v5, 0x3fb8aa3b, v35
	v_mul_f32_e32 v14, 0x3fb8aa3b, v50
	v_exp_f32_e32 v5, v5
	v_exp_f32_e32 v14, v14
	v_cvt_pk_bf16_f32 v1, v1, s0
	ds_write_b16 v54, v1 offset:22080
	v_sub_f32_e32 v1, 1.0, v5
	v_mul_f32_e32 v5, v14, v36
	v_sub_f32_e32 v14, v53, v50
	v_mul_f32_e32 v14, 0x3fb8aa3b, v14
	v_cvt_pk_bf16_f32 v5, v5, s0
	v_exp_f32_e32 v14, v14
	ds_write_b16 v54, v5 offset:1760
	v_mul_f32_e32 v5, 0x3fb8aa3b, v37
	v_exp_f32_e32 v5, v5
	v_mul_f32_e32 v1, v1, v14
	v_cvt_pk_bf16_f32 v1, v1, s0
	ds_write_b16 v54, v1 offset:22240
	v_sub_f32_e32 v1, 1.0, v5
	v_mul_f32_e32 v5, 0x3fb8aa3b, v51
	v_exp_f32_e32 v5, v5
	v_sub_f32_e32 v14, v53, v51
	v_mul_f32_e32 v14, 0x3fb8aa3b, v14
	v_exp_f32_e32 v14, v14
	v_mul_f32_e32 v5, v5, v38
	v_cvt_pk_bf16_f32 v5, v5, s0
	ds_write_b16 v54, v5 offset:1920
	v_mul_f32_e32 v1, v1, v14
	v_mul_f32_e32 v5, 0x3fb8aa3b, v39
	v_mul_f32_e32 v14, 0x3fb8aa3b, v52
	v_exp_f32_e32 v5, v5
	v_exp_f32_e32 v14, v14
	v_cvt_pk_bf16_f32 v1, v1, s0
	ds_write_b16 v54, v1 offset:22400
	v_sub_f32_e32 v1, 1.0, v5
	v_mul_f32_e32 v5, v14, v41
	v_sub_f32_e32 v14, v53, v52
	v_mul_f32_e32 v14, 0x3fb8aa3b, v14
	v_cvt_pk_bf16_f32 v5, v5, s0
	v_exp_f32_e32 v14, v14
	ds_write_b16 v54, v5 offset:2080
	v_mul_f32_e32 v5, 0x3fb8aa3b, v40
	v_exp_f32_e32 v5, v5
	v_mul_f32_e32 v1, v1, v14
	v_cvt_pk_bf16_f32 v1, v1, s0
	ds_write_b16 v54, v1 offset:22560
	v_sub_f32_e32 v1, 1.0, v5
	v_mul_f32_e32 v5, 0x3fb8aa3b, v53
	v_exp_f32_e32 v14, v5
	v_sub_f32_e32 v5, v53, v53
	v_mul_f32_e32 v5, 0x3fb8aa3b, v5
	v_exp_f32_e32 v5, v5
	v_mul_f32_e32 v16, v14, v42
	v_add_u32_e32 v2, 32, v2
	s_movk_i32 s8, 0xa0
	v_mul_f32_e32 v1, v1, v5
	v_lshl_add_u32 v5, v0, 2, 32
	v_cvt_pk_bf16_f32 v16, v16, s0
	v_cvt_pk_bf16_f32 v1, v1, s0
	ds_write_b32 v5, v14 offset:40960
	v_mad_u64_u32 v[14:15], s[12:13], v15, s8, v[2:3]
	ds_write_b16 v54, v16 offset:2240
	ds_write_b16 v54, v1 offset:22720
	s_waitcnt vmcnt(1)
	ds_write_b128 v14, v[6:9] offset:30720
	v_mad_u64_u32 v[6:7], s[12:13], v17, s8, v[2:3]
	s_mul_i32 s12, s11, 0x44
	s_waitcnt vmcnt(0)
	ds_write_b128 v6, v[10:13] offset:30720
	s_waitcnt lgkmcnt(0)
	s_barrier
	s_and_saveexec_b64 s[4:5], vcc
	s_xor_b64 s[4:5], exec, s[4:5]
	s_add_i32 s13, s12, s7
	s_or_saveexec_b64 s[4:5], s[4:5]
	v_mov_b32_e32 v1, s13
	s_xor_b64 exec, exec, s[4:5]
	s_cbranch_execz .LBB0_556
	ds_read2st64_b32 v[6:7], v5 offset0:160 offset1:161
	s_add_i32 s22, s12, s7
	s_lshl_b32 s12, s22, 8
	v_readlane_b32 s8, v252, 9
	s_add_u32 s12, s8, s12
	s_waitcnt lgkmcnt(0)
	v_mul_f32_e32 v2, v6, v7
	ds_read2st64_b32 v[6:7], v5 offset0:162 offset1:163
	v_readlane_b32 s8, v252, 10
	v_ashrrev_i32_e32 v1, 31, v0
	s_addc_u32 s13, s8, 0
	s_waitcnt lgkmcnt(0)
	v_mul_f32_e32 v2, v2, v6
	v_mul_f32_e32 v2, v2, v7
	v_lshl_add_u64 v[6:7], v[0:1], 2, s[12:13]
	v_mov_b32_e32 v1, s22
	global_store_dword v[6:7], v2, off
.LBB0_556:
	s_or_b64 exec, exec, s[4:5]
	v_bfe_u32 v6, v0, 2, 4
	v_lshlrev_b32_e32 v5, 2, v0
	v_mul_u32_u24_e32 v6, 0x50, v6
	v_lshlrev_b32_e32 v2, 12, v1
	v_lshrrev_b32_e32 v1, 2, v0
	v_and_or_b32 v5, v5, 12, v6
	v_and_b32_e32 v1, 12, v1
	v_lshlrev_b32_e32 v4, 5, v4
	v_lshlrev_b32_e32 v6, 1, v5
	v_lshl_add_u32 v26, v1, 2, 32
	v_add3_u32 v8, 32, v4, v6
	ds_read_b64_tr_b16 v[4:5], v8 offset:30720
	ds_read_b128 v[10:13], v26 offset:40960
	v_add_u32_e32 v25, 32, v6
	v_mov_b32_e32 v16, v3
	v_mov_b32_e32 v17, v3
	ds_read_b64_tr_b16 v[14:15], v25 offset:20480
	ds_read_b64_tr_b16 v[18:19], v25 offset:20512
	v_mov_b32_e32 v6, v3
	v_mov_b32_e32 v7, v3
	s_waitcnt lgkmcnt(2)
	v_pk_mul_f32 v[12:13], v[12:13], 0 op_sel_hi:[1,0]
	v_pk_mul_f32 v[10:11], v[10:11], 0 op_sel_hi:[1,0]
	v_mov_b32_e32 v20, v3
	v_mov_b32_e32 v21, v3
	s_waitcnt lgkmcnt(1)
	v_mfma_f32_16x16x32_bf16 v[10:13], v[14:17], v[4:7], v[10:13]
	ds_read_b128 v[14:17], v26 offset:41024
	ds_read_b64_tr_b16 v[28:29], v25 offset:20544
	ds_read_b64_tr_b16 v[32:33], v25 offset:20576
	v_mov_b32_e32 v30, v3
	v_mov_b32_e32 v31, v3
	s_waitcnt lgkmcnt(2)
	v_pk_mul_f32 v[16:17], v[16:17], 0 op_sel_hi:[1,0]
	v_pk_mul_f32 v[14:15], v[14:15], 0 op_sel_hi:[1,0]
	v_mov_b32_e32 v34, v3
	v_mov_b32_e32 v35, v3
	v_mfma_f32_16x16x32_bf16 v[14:17], v[18:21], v[4:7], v[14:17]
	ds_read_b128 v[18:21], v26 offset:41088
	v_and_or_b32 v0, v0, 15, v24
	v_lshl_add_u32 v0, v1, 6, v0
	v_ashrrev_i32_e32 v1, 31, v0
	s_lshl_b32 s22, s10, 1
	s_waitcnt lgkmcnt(0)
	v_pk_mul_f32 v[20:21], v[20:21], 0 op_sel_hi:[1,0]
	v_pk_mul_f32 v[18:19], v[18:19], 0 op_sel_hi:[1,0]
	s_nop 1
	v_mfma_f32_16x16x32_bf16 v[18:21], v[28:31], v[4:7], v[18:21]
	ds_read_b128 v[28:31], v26 offset:41152
	s_waitcnt lgkmcnt(0)
	v_pk_mul_f32 v[30:31], v[30:31], 0 op_sel_hi:[1,0]
	v_pk_mul_f32 v[28:29], v[28:29], 0 op_sel_hi:[1,0]
	s_nop 1
	v_mfma_f32_16x16x32_bf16 v[4:7], v[32:35], v[4:7], v[28:31]
	ds_read_b128 v[32:35], v26 offset:41216
	s_waitcnt lgkmcnt(0)
	v_pk_mul_f32 v[10:11], v[10:11], v[32:33]
	ds_read_b64_tr_b16 v[28:29], v8 offset:33280
	ds_read_b64_tr_b16 v[32:33], v25 offset:23040
	v_pk_mul_f32 v[12:13], v[12:13], v[34:35]
	v_mov_b32_e32 v34, v3
	v_mov_b32_e32 v35, v3
	v_mov_b32_e32 v30, v3
	v_mov_b32_e32 v31, v3
	s_waitcnt lgkmcnt(0)
	s_nop 0
	v_mfma_f32_16x16x32_bf16 v[10:13], v[32:35], v[28:31], v[10:13]
	ds_read_b128 v[32:35], v26 offset:41280
	s_waitcnt lgkmcnt(0)
	v_pk_mul_f32 v[14:15], v[14:15], v[32:33]
	ds_read_b64_tr_b16 v[32:33], v25 offset:23072
	v_pk_mul_f32 v[16:17], v[16:17], v[34:35]
	v_mov_b32_e32 v34, v3
	v_mov_b32_e32 v35, v3
	s_waitcnt lgkmcnt(0)
	s_nop 0
	v_mfma_f32_16x16x32_bf16 v[14:17], v[32:35], v[28:31], v[14:17]
	ds_read_b128 v[32:35], v26 offset:41344
	s_waitcnt lgkmcnt(0)
	v_pk_mul_f32 v[18:19], v[18:19], v[32:33]
	ds_read_b64_tr_b16 v[32:33], v25 offset:23104
	v_pk_mul_f32 v[20:21], v[20:21], v[34:35]
	v_mov_b32_e32 v34, v3
	v_mov_b32_e32 v35, v3
	s_waitcnt lgkmcnt(0)
	s_nop 0
	v_mfma_f32_16x16x32_bf16 v[32:35], v[32:35], v[28:31], v[18:21]
	s_nop 2
	ds_read_b128 v[18:21], v26 offset:41408
	s_waitcnt lgkmcnt(0)
	v_pk_mul_f32 v[4:5], v[4:5], v[18:19]
	ds_read_b64_tr_b16 v[18:19], v25 offset:23136
	v_pk_mul_f32 v[6:7], v[6:7], v[20:21]
	v_mov_b32_e32 v20, v3
	v_mov_b32_e32 v21, v3
	s_waitcnt lgkmcnt(0)
	s_nop 0
	v_mfma_f32_16x16x32_bf16 v[4:7], v[18:21], v[28:31], v[4:7]
	ds_read_b64_tr_b16 v[28:29], v8 offset:35840
	ds_read_b128 v[18:21], v26 offset:41472
	ds_read_b64_tr_b16 v[8:9], v8 offset:38400
	s_waitcnt lgkmcnt(1)
	v_pk_mul_f32 v[10:11], v[10:11], v[18:19]
	ds_read_b64_tr_b16 v[18:19], v25 offset:25600
	v_pk_mul_f32 v[12:13], v[12:13], v[20:21]
	v_mov_b32_e32 v20, v3
	v_mov_b32_e32 v21, v3
	s_waitcnt lgkmcnt(0)
	s_nop 0
	v_mfma_f32_16x16x32_bf16 v[20:23], v[18:21], v[28:31], v[10:13]
	s_nop 2
	ds_read_b128 v[10:13], v26 offset:41536
	s_waitcnt lgkmcnt(0)
	v_pk_mul_f32 v[10:11], v[14:15], v[10:11]
	ds_read_b64_tr_b16 v[14:15], v25 offset:25632
	v_pk_mul_f32 v[12:13], v[16:17], v[12:13]
	v_mov_b32_e32 v16, v3
	v_mov_b32_e32 v17, v3
	s_waitcnt lgkmcnt(0)
	s_nop 0
	v_mfma_f32_16x16x32_bf16 v[16:19], v[14:17], v[28:31], v[10:13]
	s_nop 2
	ds_read_b128 v[10:13], v26 offset:41600
	s_waitcnt lgkmcnt(0)
	v_pk_mul_f32 v[10:11], v[32:33], v[10:11]
	ds_read_b64_tr_b16 v[32:33], v25 offset:25664
	v_pk_mul_f32 v[12:13], v[34:35], v[12:13]
	v_mov_b32_e32 v34, v3
	v_mov_b32_e32 v35, v3
	s_waitcnt lgkmcnt(0)
	s_nop 0
	v_mfma_f32_16x16x32_bf16 v[12:15], v[32:35], v[28:31], v[10:13]
	ds_read_b128 v[32:35], v26 offset:41664
	s_nop 1
	v_mov_b32_e32 v10, v3
	v_mov_b32_e32 v11, v3
	s_waitcnt lgkmcnt(0)
	v_pk_mul_f32 v[4:5], v[4:5], v[32:33]
	ds_read_b64_tr_b16 v[32:33], v25 offset:25696
	v_pk_mul_f32 v[6:7], v[6:7], v[34:35]
	v_mov_b32_e32 v34, v3
	v_mov_b32_e32 v35, v3
	s_waitcnt lgkmcnt(0)
	s_nop 0
	v_mfma_f32_16x16x32_bf16 v[4:7], v[32:35], v[28:31], v[4:7]
	ds_read_b128 v[28:31], v26 offset:41728
	s_waitcnt lgkmcnt(0)
	v_pk_mul_f32 v[20:21], v[20:21], v[28:29]
	ds_read_b64_tr_b16 v[28:29], v25 offset:28160
	v_pk_mul_f32 v[22:23], v[22:23], v[30:31]
	v_mov_b32_e32 v30, v3
	v_mov_b32_e32 v31, v3
	s_waitcnt lgkmcnt(0)
	s_nop 0
	v_mfma_f32_16x16x32_bf16 v[20:23], v[28:31], v[8:11], v[20:23]
	ds_read_b128 v[28:31], v26 offset:41792
	s_waitcnt lgkmcnt(0)
	v_pk_mul_f32 v[16:17], v[16:17], v[28:29]
	ds_read_b64_tr_b16 v[28:29], v25 offset:28192
	v_pk_mul_f32 v[18:19], v[18:19], v[30:31]
	v_mov_b32_e32 v30, v3
	v_mov_b32_e32 v31, v3
	s_waitcnt lgkmcnt(0)
	s_nop 0
	v_mfma_f32_16x16x32_bf16 v[16:19], v[28:31], v[8:11], v[16:19]
	ds_read_b128 v[28:31], v26 offset:41856
	s_waitcnt lgkmcnt(0)
	v_pk_mul_f32 v[12:13], v[12:13], v[28:29]
	ds_read_b64_tr_b16 v[28:29], v25 offset:28224
	v_pk_mul_f32 v[14:15], v[14:15], v[30:31]
	v_mov_b32_e32 v30, v3
	v_mov_b32_e32 v31, v3
	s_waitcnt lgkmcnt(0)
	s_nop 0
	v_mfma_f32_16x16x32_bf16 v[12:15], v[28:31], v[8:11], v[12:15]
	ds_read_b128 v[26:29], v26 offset:41920
	s_waitcnt lgkmcnt(0)
	v_pk_mul_f32 v[4:5], v[4:5], v[26:27]
	ds_read_b64_tr_b16 v[26:27], v25 offset:28256
	v_pk_mul_f32 v[6:7], v[6:7], v[28:29]
	v_mov_b32_e32 v28, v3
	v_mov_b32_e32 v29, v3
	s_waitcnt lgkmcnt(0)
	s_nop 0
	v_mfma_f32_16x16x32_bf16 v[4:7], v[26:29], v[8:11], v[4:7]
	v_lshl_add_u64 v[8:9], v[2:3], 2, s[2:3]
	v_lshl_add_u64 v[10:11], v[0:1], 2, v[8:9]
	global_store_dword v[10:11], v20, off
	global_store_dword v[10:11], v21, off offset:256
	global_store_dword v[10:11], v22, off offset:512
	global_store_dword v[10:11], v23, off offset:768
	v_add_u32_e32 v10, 0x400, v0
	v_ashrrev_i32_e32 v11, 31, v10
	v_lshl_add_u64 v[10:11], v[10:11], 2, v[8:9]
	global_store_dword v[10:11], v16, off
	v_add_u32_e32 v10, 0x440, v0
	v_ashrrev_i32_e32 v11, 31, v10
	v_lshl_add_u64 v[10:11], v[10:11], 2, v[8:9]
	global_store_dword v[10:11], v17, off
	v_add_u32_e32 v10, 0x480, v0
	v_ashrrev_i32_e32 v11, 31, v10
	v_lshl_add_u64 v[10:11], v[10:11], 2, v[8:9]
	global_store_dword v[10:11], v18, off
	v_add_u32_e32 v10, 0x4c0, v0
	v_ashrrev_i32_e32 v11, 31, v10
	v_lshl_add_u64 v[10:11], v[10:11], 2, v[8:9]
	global_store_dword v[10:11], v19, off
	v_add_u32_e32 v10, 0x800, v0
	v_ashrrev_i32_e32 v11, 31, v10
	v_lshl_add_u64 v[10:11], v[10:11], 2, v[8:9]
	global_store_dword v[10:11], v12, off
	v_add_u32_e32 v10, 0x840, v0
	v_ashrrev_i32_e32 v11, 31, v10
	v_lshl_add_u64 v[10:11], v[10:11], 2, v[8:9]
	global_store_dword v[10:11], v13, off
	v_add_u32_e32 v10, 0x880, v0
	v_ashrrev_i32_e32 v11, 31, v10
	v_lshl_add_u64 v[10:11], v[10:11], 2, v[8:9]
	global_store_dword v[10:11], v14, off
	v_add_u32_e32 v10, 0x8c0, v0
	v_ashrrev_i32_e32 v11, 31, v10
	v_lshl_add_u64 v[10:11], v[10:11], 2, v[8:9]
	global_store_dword v[10:11], v15, off
	v_add_u32_e32 v10, 0xc00, v0
	v_ashrrev_i32_e32 v11, 31, v10
	v_lshl_add_u64 v[10:11], v[10:11], 2, v[8:9]
	global_store_dword v[10:11], v4, off
	v_add_u32_e32 v10, 0xc40, v0
	v_ashrrev_i32_e32 v11, 31, v10
	v_add_u32_e32 v4, 0xc80, v0
	v_add_u32_e32 v0, 0xcc0, v0
	v_lshl_add_u64 v[10:11], v[10:11], 2, v[8:9]
	v_ashrrev_i32_e32 v1, 31, v0
	global_store_dword v[10:11], v5, off
	v_ashrrev_i32_e32 v5, 31, v4
	v_lshl_add_u64 v[0:1], v[0:1], 2, v[8:9]
	v_lshl_add_u64 v[4:5], v[4:5], 2, v[8:9]
	global_store_dword v[0:1], v7, off
	v_mov_b32_e32 v0, v222
	global_store_dword v[4:5], v6, off
	s_nop 0
	v_and_b32_e32 v4, 63, v0
	v_or_b32_e32 v1, s10, v4
	v_ashrrev_i32_e32 v10, 6, v0
	v_lshlrev_b32_e32 v2, 1, v1
	v_lshlrev_b32_e32 v24, 4, v10
	v_lshl_add_u64 v[6:7], s[0:1], 0, v[2:3]
	v_mad_i64_i32 v[8:9], s[4:5], v24, s48, v[6:7]
	s_barrier
	v_mov_b32_e32 v1, v80
	v_or_b32_e32 v42, 1, v24
	v_or_b32_e32 v2, 11, v24
	v_or_b32_e32 v11, 13, v24
	v_or_b32_e32 v27, 15, v24
	v_cmp_lt_i32_e32 vcc, 63, v0
	s_waitcnt vmcnt(0)
	v_lshlrev_b32_e32 v33, 16, v1
	v_mov_b32_e32 v1, v96
	v_mad_i64_i32 v[8:9], s[4:5], v42, s48, v[6:7]
	s_waitcnt vmcnt(0)
	v_lshlrev_b32_e32 v45, 16, v1
	v_mov_b32_e32 v1, v81
	s_waitcnt vmcnt(0)
	v_lshlrev_b32_e32 v43, 16, v1
	v_mov_b32_e32 v1, v97
	s_waitcnt vmcnt(0)
	v_lshlrev_b32_e32 v41, 16, v1
	v_or_b32_e32 v1, 2, v24
	v_mad_i64_i32 v[8:9], s[4:5], v1, s48, v[6:7]
	v_mov_b32_e32 v1, v82
	s_waitcnt vmcnt(0)
	v_lshlrev_b32_e32 v39, 16, v1
	v_mov_b32_e32 v1, v98
	s_waitcnt vmcnt(0)
	v_lshlrev_b32_e32 v38, 16, v1
	v_or_b32_e32 v1, 3, v24
	v_mad_i64_i32 v[8:9], s[4:5], v1, s48, v[6:7]
	v_mov_b32_e32 v1, v83
	s_waitcnt vmcnt(0)
	v_lshlrev_b32_e32 v37, 16, v1
	v_mov_b32_e32 v1, v99
	s_waitcnt vmcnt(0)
	v_lshlrev_b32_e32 v35, 16, v1
	v_or_b32_e32 v1, 4, v24
	v_mad_i64_i32 v[8:9], s[4:5], v1, s48, v[6:7]
	v_mov_b32_e32 v1, v84
	s_waitcnt vmcnt(0)
	v_lshlrev_b32_e32 v32, 16, v1
	v_mov_b32_e32 v1, v100
	s_waitcnt vmcnt(0)
	v_lshlrev_b32_e32 v28, 16, v1
	v_or_b32_e32 v1, 5, v24
	v_mad_i64_i32 v[8:9], s[4:5], v1, s48, v[6:7]
	v_mov_b32_e32 v1, v85
	s_waitcnt vmcnt(0)
	v_lshlrev_b32_e32 v26, 16, v1
	v_mov_b32_e32 v1, v101
	s_waitcnt vmcnt(0)
	v_lshlrev_b32_e32 v25, 16, v1
	v_or_b32_e32 v1, 6, v24
	v_mad_i64_i32 v[8:9], s[4:5], v1, s48, v[6:7]
	v_mov_b32_e32 v1, v86
	s_waitcnt vmcnt(0)
	v_lshlrev_b32_e32 v23, 16, v1
	v_mov_b32_e32 v1, v102
	s_waitcnt vmcnt(0)
	v_lshlrev_b32_e32 v22, 16, v1
	v_or_b32_e32 v1, 7, v24
	v_mad_i64_i32 v[8:9], s[4:5], v1, s48, v[6:7]
	v_mov_b32_e32 v1, v87
	s_waitcnt vmcnt(0)
	v_lshlrev_b32_e32 v21, 16, v1
	v_mov_b32_e32 v1, v103
	s_waitcnt vmcnt(0)
	v_lshlrev_b32_e32 v20, 16, v1
	v_or_b32_e32 v1, 8, v24
	v_mad_i64_i32 v[8:9], s[4:5], v1, s48, v[6:7]
	v_mov_b32_e32 v1, v88
	s_waitcnt vmcnt(0)
	v_lshlrev_b32_e32 v19, 16, v1
	v_mov_b32_e32 v1, v104
	s_waitcnt vmcnt(0)
	v_lshlrev_b32_e32 v18, 16, v1
	v_or_b32_e32 v1, 9, v24
	v_mad_i64_i32 v[8:9], s[4:5], v1, s48, v[6:7]
	v_mov_b32_e32 v1, v89
	s_waitcnt vmcnt(0)
	v_lshlrev_b32_e32 v17, 16, v1
	v_mov_b32_e32 v1, v105
	s_waitcnt vmcnt(0)
	v_lshlrev_b32_e32 v16, 16, v1
	v_or_b32_e32 v1, 10, v24
	v_mad_i64_i32 v[8:9], s[4:5], v1, s48, v[6:7]
	v_mov_b32_e32 v1, v90
	s_waitcnt vmcnt(0)
	v_lshlrev_b32_e32 v12, 16, v1
	v_mov_b32_e32 v1, v106
	v_mad_i64_i32 v[8:9], s[4:5], v2, s48, v[6:7]
	v_mov_b32_e32 v2, v91
	v_mov_b32_e32 v5, v107
	v_or_b32_e32 v8, 12, v24
	v_mad_i64_i32 v[14:15], s[4:5], v8, s48, v[6:7]
	v_mov_b32_e32 v8, v92
	s_waitcnt vmcnt(3)
	v_lshlrev_b32_e32 v1, 16, v1
	s_waitcnt vmcnt(2)
	v_lshlrev_b32_e32 v2, 16, v2
	s_waitcnt vmcnt(1)
	v_lshlrev_b32_e32 v5, 16, v5
	s_waitcnt vmcnt(0)
	v_lshlrev_b32_e32 v9, 16, v8
	v_mov_b32_e32 v8, v108
	v_mad_i64_i32 v[14:15], s[4:5], v11, s48, v[6:7]
	v_mov_b32_e32 v11, v93
	s_waitcnt vmcnt(1)
	v_lshlrev_b32_e32 v8, 16, v8
	s_waitcnt vmcnt(0)
	v_lshlrev_b32_e32 v13, 16, v11
	v_mov_b32_e32 v11, v109
	v_or_b32_e32 v14, 14, v24
	v_mad_i64_i32 v[30:31], s[4:5], v14, s48, v[6:7]
	v_mov_b32_e32 v14, v94
	s_waitcnt vmcnt(1)
	v_lshlrev_b32_e32 v11, 16, v11
	s_waitcnt vmcnt(0)
	v_lshlrev_b32_e32 v15, 16, v14
	v_mov_b32_e32 v14, v110
	v_mad_i64_i32 v[30:31], s[4:5], v27, s48, v[6:7]
	v_mov_b32_e32 v6, v95
	v_mov_b32_e32 v7, v111
	s_movk_i32 s4, 0x500
	s_waitcnt vmcnt(2)
	v_lshlrev_b32_e32 v14, 16, v14
	s_waitcnt vmcnt(1)
	v_lshlrev_b32_e32 v6, 16, v6
	s_waitcnt vmcnt(0)
	v_lshlrev_b32_e32 v27, 16, v7
	v_add_f32_e32 v7, 0, v6
	v_add_f32_e32 v29, v7, v15
	v_add_f32_e32 v31, v29, v13
	v_add_f32_e32 v34, v31, v9
	v_add_f32_e32 v36, v34, v2
	v_add_f32_e32 v40, v36, v12
	v_add_f32_e32 v44, v40, v17
	v_add_f32_e32 v46, v44, v19
	v_add_f32_e32 v47, v46, v21
	v_add_f32_e32 v48, v47, v23
	v_add_f32_e32 v49, v48, v26
	v_add_f32_e32 v50, v49, v32
	v_add_f32_e32 v51, v50, v37
	v_add_f32_e32 v52, v51, v39
	v_add_f32_e32 v53, v52, v43
	v_add_f32_e32 v30, v53, v33
	v_mul_f32_e32 v33, 0x3fb8aa3b, v33
	v_exp_f32_e32 v33, v33
	v_mul_f32_e32 v43, 0x3fb8aa3b, v43
	v_exp_f32_e32 v43, v43
	v_mul_f32_e32 v39, 0x3fb8aa3b, v39
	v_sub_f32_e32 v54, 1.0, v33
	v_mul_lo_u32 v33, v10, s4
	v_or_b32_e32 v55, v33, v4
	v_mul_f32_e32 v33, 0x3fb8aa3b, v30
	v_exp_f32_e32 v33, v33
	v_lshl_add_u32 v55, v55, 1, 32
	s_movk_i32 s4, 0x50
	v_exp_f32_e32 v39, v39
	v_mul_f32_e32 v45, v33, v45
	v_cvt_pk_bf16_f32 v45, v45, s0
	ds_write_b16 v55, v45
	v_sub_f32_e32 v45, v30, v30
	v_mul_f32_e32 v45, 0x3fb8aa3b, v45
	v_exp_f32_e32 v45, v45
	v_sub_f32_e32 v39, 1.0, v39
	v_mul_f32_e32 v37, 0x3fb8aa3b, v37
	v_exp_f32_e32 v37, v37
	v_mul_f32_e32 v45, v54, v45
	v_cvt_pk_bf16_f32 v45, v45, s0
	ds_write_b16 v55, v45 offset:20480
	v_sub_f32_e32 v45, 1.0, v43
	v_mad_u64_u32 v[42:43], s[4:5], v42, s4, v[4:5]
	v_mul_f32_e32 v4, 0x3fb8aa3b, v53
	v_exp_f32_e32 v4, v4
	v_sub_f32_e32 v37, 1.0, v37
	v_mul_f32_e32 v32, 0x3fb8aa3b, v32
	v_exp_f32_e32 v32, v32
	v_mul_f32_e32 v4, v4, v41
	v_cvt_pk_bf16_f32 v41, v4, s0
	v_lshl_add_u32 v4, v42, 1, 32
	ds_write_b16 v4, v41
	v_sub_f32_e32 v41, v30, v53
	v_mul_f32_e32 v41, 0x3fb8aa3b, v41
	v_exp_f32_e32 v41, v41
	v_sub_f32_e32 v32, 1.0, v32
	v_mul_f32_e32 v26, 0x3fb8aa3b, v26
	v_exp_f32_e32 v26, v26
	v_mul_f32_e32 v41, v45, v41
	v_cvt_pk_bf16_f32 v41, v41, s0
	ds_write_b16 v4, v41 offset:20480
	v_mul_f32_e32 v41, 0x3fb8aa3b, v52
	v_exp_f32_e32 v41, v41
	v_sub_f32_e32 v26, 1.0, v26
	v_mul_f32_e32 v23, 0x3fb8aa3b, v23
	v_exp_f32_e32 v23, v23
	v_mul_f32_e32 v38, v41, v38
	v_cvt_pk_bf16_f32 v38, v38, s0
	ds_write_b16 v4, v38 offset:160
	v_sub_f32_e32 v38, v30, v52
	v_mul_f32_e32 v38, 0x3fb8aa3b, v38
	v_exp_f32_e32 v38, v38
	v_sub_f32_e32 v23, 1.0, v23
	v_mul_f32_e32 v21, 0x3fb8aa3b, v21
	v_exp_f32_e32 v21, v21
	v_mul_f32_e32 v38, v39, v38
	v_cvt_pk_bf16_f32 v38, v38, s0
	ds_write_b16 v4, v38 offset:20640
	v_mul_f32_e32 v38, 0x3fb8aa3b, v51
	v_exp_f32_e32 v38, v38
	v_sub_f32_e32 v21, 1.0, v21
	v_mul_f32_e32 v19, 0x3fb8aa3b, v19
	v_exp_f32_e32 v19, v19
	v_mul_f32_e32 v35, v38, v35
	v_cvt_pk_bf16_f32 v35, v35, s0
	ds_write_b16 v4, v35 offset:320
	v_sub_f32_e32 v35, v30, v51
	v_mul_f32_e32 v35, 0x3fb8aa3b, v35
	v_exp_f32_e32 v35, v35
	v_sub_f32_e32 v19, 1.0, v19
	v_mul_f32_e32 v17, 0x3fb8aa3b, v17
	v_exp_f32_e32 v17, v17
	v_mul_f32_e32 v35, v37, v35
	v_cvt_pk_bf16_f32 v35, v35, s0
	ds_write_b16 v4, v35 offset:20800
	v_mul_f32_e32 v35, 0x3fb8aa3b, v50
	v_exp_f32_e32 v35, v35
	v_sub_f32_e32 v17, 1.0, v17
	v_mul_f32_e32 v12, 0x3fb8aa3b, v12
	v_exp_f32_e32 v12, v12
	v_mul_f32_e32 v28, v35, v28
	v_cvt_pk_bf16_f32 v28, v28, s0
	ds_write_b16 v4, v28 offset:480
	v_sub_f32_e32 v28, v30, v50
	v_mul_f32_e32 v28, 0x3fb8aa3b, v28
	v_exp_f32_e32 v28, v28
	v_sub_f32_e32 v12, 1.0, v12
	s_movk_i32 s4, 0xa0
	v_mul_f32_e32 v28, v32, v28
	v_cvt_pk_bf16_f32 v28, v28, s0
	ds_write_b16 v4, v28 offset:20960
	v_mul_f32_e32 v28, 0x3fb8aa3b, v49
	v_exp_f32_e32 v28, v28
	s_nop 0
	v_mul_f32_e32 v25, v28, v25
	v_cvt_pk_bf16_f32 v25, v25, s0
	ds_write_b16 v4, v25 offset:640
	v_sub_f32_e32 v25, v30, v49
	v_mul_f32_e32 v25, 0x3fb8aa3b, v25
	v_exp_f32_e32 v25, v25
	s_nop 0
	v_mul_f32_e32 v25, v26, v25
	v_cvt_pk_bf16_f32 v25, v25, s0
	ds_write_b16 v4, v25 offset:21120
	v_mul_f32_e32 v25, 0x3fb8aa3b, v48
	v_exp_f32_e32 v25, v25
	s_nop 0
	v_mul_f32_e32 v22, v25, v22
	v_cvt_pk_bf16_f32 v22, v22, s0
	ds_write_b16 v4, v22 offset:800
	v_sub_f32_e32 v22, v30, v48
	v_mul_f32_e32 v22, 0x3fb8aa3b, v22
	v_exp_f32_e32 v22, v22
	s_nop 0
	v_mul_f32_e32 v22, v23, v22
	v_cvt_pk_bf16_f32 v22, v22, s0
	ds_write_b16 v4, v22 offset:21280
	v_mul_f32_e32 v22, 0x3fb8aa3b, v47
	v_exp_f32_e32 v22, v22
	s_nop 0
	v_mul_f32_e32 v20, v22, v20
	v_cvt_pk_bf16_f32 v20, v20, s0
	ds_write_b16 v4, v20 offset:960
	v_sub_f32_e32 v20, v30, v47
	v_mul_f32_e32 v20, 0x3fb8aa3b, v20
	v_exp_f32_e32 v20, v20
	s_nop 0
	v_mul_f32_e32 v20, v21, v20
	v_cvt_pk_bf16_f32 v20, v20, s0
	ds_write_b16 v4, v20 offset:21440
	v_mul_f32_e32 v20, 0x3fb8aa3b, v46
	v_exp_f32_e32 v20, v20
	s_nop 0
	v_mul_f32_e32 v18, v20, v18
	v_cvt_pk_bf16_f32 v18, v18, s0
	ds_write_b16 v4, v18 offset:1120
	v_sub_f32_e32 v18, v30, v46
	v_mul_f32_e32 v18, 0x3fb8aa3b, v18
	v_exp_f32_e32 v18, v18
	s_nop 0
	v_mul_f32_e32 v18, v19, v18
	v_cvt_pk_bf16_f32 v18, v18, s0
	ds_write_b16 v4, v18 offset:21600
	v_mul_f32_e32 v18, 0x3fb8aa3b, v44
	v_exp_f32_e32 v18, v18
	s_nop 0
	v_mul_f32_e32 v16, v18, v16
	v_cvt_pk_bf16_f32 v16, v16, s0
	ds_write_b16 v4, v16 offset:1280
	v_sub_f32_e32 v16, v30, v44
	v_mul_f32_e32 v16, 0x3fb8aa3b, v16
	v_exp_f32_e32 v16, v16
	s_nop 0
	v_mul_f32_e32 v16, v17, v16
	v_cvt_pk_bf16_f32 v16, v16, s0
	ds_write_b16 v4, v16 offset:21760
	v_mul_f32_e32 v16, 0x3fb8aa3b, v40
	v_exp_f32_e32 v16, v16
	s_nop 0
	v_mul_f32_e32 v1, v16, v1
	v_cvt_pk_bf16_f32 v1, v1, s0
	ds_write_b16 v4, v1 offset:1440
	v_sub_f32_e32 v1, v30, v40
	v_mul_f32_e32 v1, 0x3fb8aa3b, v1
	v_exp_f32_e32 v1, v1
	s_nop 0
	v_mul_f32_e32 v1, v12, v1
	v_cvt_pk_bf16_f32 v1, v1, s0
	ds_write_b16 v4, v1 offset:21920
	v_mul_f32_e32 v1, 0x3fb8aa3b, v2
	v_mul_f32_e32 v2, 0x3fb8aa3b, v36
	v_exp_f32_e32 v2, v2
	v_exp_f32_e32 v1, v1
	v_mul_f32_e32 v2, v2, v5
	v_cvt_pk_bf16_f32 v2, v2, s0
	ds_write_b16 v4, v2 offset:1600
	v_sub_f32_e32 v2, v30, v36
	v_mul_f32_e32 v2, 0x3fb8aa3b, v2
	v_exp_f32_e32 v2, v2
	v_sub_f32_e32 v1, 1.0, v1
	v_mul_f32_e32 v1, v1, v2
	v_mul_f32_e32 v2, 0x3fb8aa3b, v34
	v_exp_f32_e32 v2, v2
	v_cvt_pk_bf16_f32 v1, v1, s0
	ds_write_b16 v4, v1 offset:22080
	v_mul_f32_e32 v1, 0x3fb8aa3b, v9
	v_mul_f32_e32 v2, v2, v8
	v_cvt_pk_bf16_f32 v2, v2, s0
	ds_write_b16 v4, v2 offset:1760
	v_sub_f32_e32 v2, v30, v34
	v_exp_f32_e32 v1, v1
	v_mul_f32_e32 v2, 0x3fb8aa3b, v2
	v_exp_f32_e32 v2, v2
	v_sub_f32_e32 v1, 1.0, v1
	v_mul_f32_e32 v1, v1, v2
	v_mul_f32_e32 v2, 0x3fb8aa3b, v31
	v_exp_f32_e32 v2, v2
	v_cvt_pk_bf16_f32 v1, v1, s0
	ds_write_b16 v4, v1 offset:22240
	v_mul_f32_e32 v1, 0x3fb8aa3b, v13
	v_mul_f32_e32 v2, v2, v11
	v_cvt_pk_bf16_f32 v2, v2, s0
	ds_write_b16 v4, v2 offset:1920
	v_sub_f32_e32 v2, v30, v31
	v_exp_f32_e32 v1, v1
	v_mul_f32_e32 v2, 0x3fb8aa3b, v2
	v_exp_f32_e32 v2, v2
	v_mov_b64_e32 v[12:13], s[0:1]
	v_sub_f32_e32 v1, 1.0, v1
	v_lshl_add_u32 v11, v0, 2, 32
	v_mul_f32_e32 v1, v1, v2
	v_mul_f32_e32 v2, 0x3fb8aa3b, v29
	v_exp_f32_e32 v2, v2
	v_cvt_pk_bf16_f32 v1, v1, s0
	ds_write_b16 v4, v1 offset:22400
	v_mul_f32_e32 v1, 0x3fb8aa3b, v15
	v_mul_f32_e32 v2, v2, v14
	v_cvt_pk_bf16_f32 v2, v2, s0
	ds_write_b16 v4, v2 offset:2080
	v_sub_f32_e32 v2, v30, v29
	v_exp_f32_e32 v1, v1
	v_mul_f32_e32 v2, 0x3fb8aa3b, v2
	v_exp_f32_e32 v2, v2
	ds_write_b32 v11, v33 offset:40960
	v_sub_f32_e32 v1, 1.0, v1
	v_mul_f32_e32 v1, v1, v2
	v_mul_f32_e32 v2, 0x3fb8aa3b, v7
	v_exp_f32_e32 v2, v2
	v_cvt_pk_bf16_f32 v1, v1, s0
	ds_write_b16 v4, v1 offset:22560
	v_mul_f32_e32 v1, 0x3fb8aa3b, v6
	v_mul_f32_e32 v2, v2, v27
	v_cvt_pk_bf16_f32 v2, v2, s0
	ds_write_b16 v4, v2 offset:2240
	v_sub_f32_e32 v2, v30, v7
	v_exp_f32_e32 v1, v1
	v_mul_f32_e32 v2, 0x3fb8aa3b, v2
	v_exp_f32_e32 v2, v2
	v_sub_f32_e32 v1, 1.0, v1
	v_mul_f32_e32 v1, v1, v2
	v_cvt_pk_bf16_f32 v1, v1, s0
	ds_write_b16 v4, v1 offset:22720
	v_lshlrev_b32_e32 v1, 4, v0
	v_and_b32_e32 v2, 0x70, v1
	v_ashrrev_i32_e32 v1, 3, v0
	v_mad_i64_i32 v[4:5], s[0:1], v1, s48, v[12:13]
	v_lshl_add_u64 v[4:5], v[4:5], 0, s[22:23]
	v_lshl_add_u64 v[4:5], v[4:5], 0, v[2:3]
	v_mov_b32_e32 v4, v140
	v_mov_b32_e32 v5, v141
	v_mov_b32_e32 v6, v142
	v_mov_b32_e32 v7, v143
	v_add_u32_e32 v8, 32, v2
	v_mad_u64_u32 v[14:15], s[0:1], v1, s4, v[8:9]
	v_add_u32_e32 v1, 0x100, v0
	v_ashrrev_i32_e32 v1, 3, v1
	v_mad_u64_u32 v[8:9], s[0:1], v1, s4, v[8:9]
	s_or_b32 s4, s11, 1
	s_mulk_i32 s4, 0x44
	s_waitcnt vmcnt(0)
	ds_write_b128 v14, v[4:7] offset:30720
	v_mad_i64_i32 v[4:5], s[0:1], v1, s48, v[12:13]
	v_lshl_add_u64 v[4:5], v[4:5], 0, s[22:23]
	v_lshl_add_u64 v[4:5], v[4:5], 0, v[2:3]
	v_mov_b32_e32 v4, v144
	v_mov_b32_e32 v5, v145
	v_mov_b32_e32 v6, v146
	v_mov_b32_e32 v7, v147
	s_waitcnt vmcnt(0)
	ds_write_b128 v8, v[4:7] offset:30720
	s_waitcnt lgkmcnt(0)
	s_barrier
	s_and_saveexec_b64 s[0:1], vcc
	s_xor_b64 s[0:1], exec, s[0:1]
	s_add_i32 s5, s4, s7
	s_or_saveexec_b64 s[0:1], s[0:1]
	v_mov_b32_e32 v1, s5
	s_xor_b64 exec, exec, s[0:1]
	s_cbranch_execz .LBB0_560
	ds_read2st64_b32 v[4:5], v11 offset0:160 offset1:161
	s_add_i32 s7, s4, s7
	s_lshl_b32 s4, s7, 8
	v_readlane_b32 s5, v252, 9
	s_add_u32 s4, s5, s4
	s_waitcnt lgkmcnt(0)
	v_mul_f32_e32 v2, v4, v5
	ds_read2st64_b32 v[4:5], v11 offset0:162 offset1:163
	v_readlane_b32 s5, v252, 10
	v_ashrrev_i32_e32 v1, 31, v0
	s_addc_u32 s5, s5, 0
	s_waitcnt lgkmcnt(0)
	v_mul_f32_e32 v2, v2, v4
	v_mul_f32_e32 v2, v2, v5
	v_lshl_add_u64 v[4:5], v[0:1], 2, s[4:5]
	v_mov_b32_e32 v1, s7
	global_store_dword v[4:5], v2, off
